# barrier: arrival atomic issued before the L1 invalidate so its return is not held behind the invalidate
# baseline (speedup 1.0000x reference)
.LBB0_605:
	s_waitcnt vmcnt(0)
	s_waitcnt vmcnt(0) lgkmcnt(0)
	s_barrier
	s_and_saveexec_b64 s[4:5], s[88:89]
	v_readlane_b32 s22, v249, 57
	v_readlane_b32 s24, v249, 59
	v_readlane_b32 s26, v249, 61
	v_readlane_b32 s28, v249, 63
	v_readlane_b32 s30, v248, 1
	v_readlane_b32 s34, v248, 3
	v_readlane_b32 s36, v248, 5
	v_readlane_b32 s23, v249, 58
	v_readlane_b32 s25, v249, 60
	v_readlane_b32 s27, v249, 62
	v_readlane_b32 s29, v248, 0
	v_readlane_b32 s31, v248, 2
	v_readlane_b32 s35, v248, 4
	v_readlane_b32 s37, v248, 6
	v_readlane_b32 s21, v248, 7
	s_cbranch_execz .LBB0_133
	v_readlane_b32 s6, v249, 50
	v_readlane_b32 s7, v249, 51
	v_readlane_b32 s8, v249, 35
	v_readlane_b32 s9, v249, 36
	v_readlane_b32 s10, v249, 37
	v_readlane_b32 s11, v249, 38
	v_mov_b32_e32 v0, s6
	v_mov_b32_e32 v2, s7
	ds_read_b32 v3, v0
	ds_read_b32 v2, v2
	v_mov_b32_e32 v4, 1
	s_add_i32 s15, s3, 2
	s_nop 2
	global_atomic_add v4, v1, v4, s[8:9] sc0
	buffer_inv sc1
	s_waitcnt vmcnt(1) lgkmcnt(0)
	v_max_u32_e32 v3, 1, v3
	v_max_u32_e32 v2, 1, v2
	v_readfirstlane_b32 s12, v4
	v_readfirstlane_b32 s13, v3
	v_readfirstlane_b32 s14, v2
	s_mul_i32 s16, s15, s13
	s_add_i32 s12, s12, 1
	s_cmp_lg_u32 s12, s16
	s_cbranch_scc1 .Lb_wait
	s_bitcmp1_b32 0xd5b56, s3
	s_cbranch_scc1 .Lb_nowb
	buffer_wbl2 sc1
